# GEMM K-loops (in-proj x2, out-proj): ds_read reorder with counted waits, ds_write+global_load interleaved into last MFMA group
# speedup vs baseline: 1.0120x; 1.0120x over previous
; #define MFMA32(a, b, c) __builtin_amdgcn_mfma_f32_32x32x16_bf16((a), (b), (c), 0, 0, 0)
; #define G_LOAD(KT) do { const int k0_ = (KT) << 6; _Pragma("unroll") for (int p = 0; p < 4; ++p) { \
;     ra[p] = *(const u32x4*)(ap + (size_t)(64 * p) * lda + k0_); rb[p] = *(const u32x4*)(bp + (size_t)(64 * p) * ldb + k0_); } } while (0)
; template <bool SWAP, bool SSQ, bool ZERO = true>
; DI void gemm_main(const u16* __restrict__ A, int lda, const u16* __restrict__ Bt, int ldb, int K, char* lds,
;                   f32x16 (&acc)[4][2], float* rs_lds) {
;     ...
;   for (int kt = 0; kt < nk; ++kt) {
;     const int st = (kt & 1) * 2 * G_TILE;
;     {
;       bf16x8 fa[2][4], fb[2][2];
; #pragma unroll
;       for (int i = 0; i < 4; ++i) fa[0][i] = *(const bf16x8*)(abase + st + i * 32 * GS);
; #pragma unroll
;       for (int i = 0; i < 2; ++i) fb[0][i] = *(const bf16x8*)(bbase + st + i * 32 * GS);
; #pragma unroll
;       for (int ks = 0; ks < 4; ++ks) {
;         if (ks + 1 < 4) {
; #pragma unroll
;           for (int i = 0; i < 4; ++i) fa[(ks + 1) & 1][i] = *(const bf16x8*)(abase + st + i * 32 * GS + (ks + 1) * 32);
; #pragma unroll
;           for (int i = 0; i < 2; ++i) fb[(ks + 1) & 1][i] = *(const bf16x8*)(bbase + st + i * 32 * GS + (ks + 1) * 32);
;         }
;         __builtin_amdgcn_sched_barrier(0);
;         __builtin_amdgcn_s_setprio(1);
; #pragma unroll
;         for (int mt = 0; mt < 4; ++mt)
; #pragma unroll
;           for (int nt = 0; nt < 2; ++nt)
;             acc[mt][nt] = SWAP ? MFMA32(fb[ks & 1][nt], fa[ks & 1][mt], acc[mt][nt]) : MFMA32(fa[ks & 1][mt], fb[ks & 1][nt], acc[mt][nt]);
;         __builtin_amdgcn_s_setprio(0);
;         __builtin_amdgcn_sched_barrier(0);
;       }
;     }
;     if (kt + 1 < nk) G_WRITE((kt + 1) & 1);
;     if (kt + 2 < nk) G_LOAD(kt + 2);
;     __syncthreads();
;   }
.LBB0_292:
	s_add_i32 s4, s85, -2
	s_and_b32 s4, s4, 2
	s_mul_i32 s4, s4, 0x9000
	v_add_u32_e32 v177, s4, v176
	v_add_u32_e32 v240, s4, v175
	ds_read_b128 v[214:217], v240 offset:36864
	ds_read_b128 v[182:185], v177
	ds_read_b128 v[232:235], v240 offset:41472
	ds_read_b128 v[190:193], v177 offset:4608
	ds_read_b128 v[198:201], v177 offset:9216
	ds_read_b128 v[206:209], v177 offset:13824
	ds_read_b128 v[218:221], v240 offset:36896
	ds_read_b128 v[186:189], v177 offset:32
	ds_read_b128 v[236:239], v240 offset:41504
	ds_read_b128 v[194:197], v177 offset:4640
	ds_read_b128 v[202:205], v177 offset:9248
	ds_read_b128 v[210:213], v177 offset:13856
	s_setprio 1
	s_waitcnt lgkmcnt(10)
	v_mfma_f32_32x32x16_bf16 v[114:129], v[214:217], v[182:185], v[114:129]
	s_waitcnt lgkmcnt(9)
	v_mfma_f32_32x32x16_bf16 v[98:113], v[232:235], v[182:185], v[98:113]
	s_waitcnt lgkmcnt(8)
	v_mfma_f32_32x32x16_bf16 v[82:97], v[214:217], v[190:193], v[82:97]
	v_mfma_f32_32x32x16_bf16 v[66:81], v[232:235], v[190:193], v[66:81]
	s_waitcnt lgkmcnt(7)
	v_mfma_f32_32x32x16_bf16 v[50:65], v[214:217], v[198:201], v[50:65]
	v_mfma_f32_32x32x16_bf16 v[34:49], v[232:235], v[198:201], v[34:49]
	s_waitcnt lgkmcnt(6)
	v_mfma_f32_32x32x16_bf16 v[18:33], v[214:217], v[206:209], v[18:33]
	v_mfma_f32_32x32x16_bf16 v[2:17], v[232:235], v[206:209], v[2:17]
	s_setprio 0
	ds_read_b128 v[214:217], v240 offset:36928
	ds_read_b128 v[182:185], v177 offset:64
	ds_read_b128 v[232:235], v240 offset:41536
	ds_read_b128 v[190:193], v177 offset:4672
	ds_read_b128 v[198:201], v177 offset:9280
	ds_read_b128 v[206:209], v177 offset:13888
	s_setprio 1
	s_waitcnt lgkmcnt(10)
	v_mfma_f32_32x32x16_bf16 v[114:129], v[218:221], v[186:189], v[114:129]
	s_waitcnt lgkmcnt(9)
	v_mfma_f32_32x32x16_bf16 v[98:113], v[236:239], v[186:189], v[98:113]
	s_waitcnt lgkmcnt(8)
	v_mfma_f32_32x32x16_bf16 v[82:97], v[218:221], v[194:197], v[82:97]
	v_mfma_f32_32x32x16_bf16 v[66:81], v[236:239], v[194:197], v[66:81]
	s_waitcnt lgkmcnt(7)
	v_mfma_f32_32x32x16_bf16 v[50:65], v[218:221], v[202:205], v[50:65]
	v_mfma_f32_32x32x16_bf16 v[34:49], v[236:239], v[202:205], v[34:49]
	s_waitcnt lgkmcnt(6)
	v_mfma_f32_32x32x16_bf16 v[18:33], v[218:221], v[210:213], v[18:33]
	v_mfma_f32_32x32x16_bf16 v[2:17], v[236:239], v[210:213], v[2:17]
	s_setprio 0
	ds_read_b128 v[218:221], v240 offset:36960
	ds_read_b128 v[186:189], v177 offset:96
	ds_read_b128 v[236:239], v240 offset:41568
	ds_read_b128 v[194:197], v177 offset:4704
	ds_read_b128 v[202:205], v177 offset:9312
	ds_read_b128 v[210:213], v177 offset:13920
	s_setprio 1
	s_waitcnt lgkmcnt(10)
	v_mfma_f32_32x32x16_bf16 v[114:129], v[214:217], v[182:185], v[114:129]
	s_waitcnt lgkmcnt(9)
	v_mfma_f32_32x32x16_bf16 v[98:113], v[232:235], v[182:185], v[98:113]
	s_waitcnt lgkmcnt(8)
	v_mfma_f32_32x32x16_bf16 v[82:97], v[214:217], v[190:193], v[82:97]
	v_mfma_f32_32x32x16_bf16 v[66:81], v[232:235], v[190:193], v[66:81]
	s_waitcnt lgkmcnt(7)
	v_mfma_f32_32x32x16_bf16 v[50:65], v[214:217], v[198:201], v[50:65]
	v_mfma_f32_32x32x16_bf16 v[34:49], v[232:235], v[198:201], v[34:49]
	s_waitcnt lgkmcnt(6)
	v_mfma_f32_32x32x16_bf16 v[18:33], v[214:217], v[206:209], v[18:33]
	v_mfma_f32_32x32x16_bf16 v[2:17], v[232:235], v[206:209], v[2:17]
	s_setprio 0
	s_cmp_gt_u32 s86, 29
	s_cbranch_scc1 .Lg292_tail
	s_setprio 1
	s_waitcnt lgkmcnt(4)
	v_mfma_f32_32x32x16_bf16 v[114:129], v[218:221], v[186:189], v[114:129]
	s_and_b32 s4, s85, 2
	s_mul_i32 s4, s4, 0x9000
	v_add_u32_e32 v242, s4, v174
	s_waitcnt lgkmcnt(3)
	v_mfma_f32_32x32x16_bf16 v[98:113], v[236:239], v[186:189], v[98:113]
	v_lshl_add_u64 v[244:245], v[180:181], 0, s[82:83]
	v_lshl_add_u64 v[246:247], v[178:179], 0, s[82:83]
	s_waitcnt lgkmcnt(0)
	v_mfma_f32_32x32x16_bf16 v[82:97], v[218:221], v[194:197], v[82:97]
	s_waitcnt vmcnt(7)
	ds_write_b128 v242, v[130:133]
	global_load_dwordx4 v[130:133], v[244:245], off offset:256
	v_mfma_f32_32x32x16_bf16 v[66:81], v[236:239], v[194:197], v[66:81]
	s_waitcnt vmcnt(7)
	ds_write_b128 v242, v[134:137] offset:36864
	global_load_dwordx4 v[134:137], v[246:247], off offset:256
	v_add_co_u32_e32 v244, vcc, 0x40000, v244
	v_mfma_f32_32x32x16_bf16 v[50:65], v[218:221], v[202:205], v[50:65]
	s_waitcnt vmcnt(7)
	ds_write_b128 v242, v[138:141] offset:9216
	v_addc_co_u32_e32 v245, vcc, 0, v245, vcc
	global_load_dwordx4 v[138:141], v[244:245], off offset:256
	v_add_co_u32_e32 v246, vcc, 0x40000, v246
	v_mfma_f32_32x32x16_bf16 v[34:49], v[236:239], v[202:205], v[34:49]
	s_waitcnt vmcnt(7)
	ds_write_b128 v242, v[142:145] offset:46080
	v_addc_co_u32_e32 v247, vcc, 0, v247, vcc
	global_load_dwordx4 v[142:145], v[246:247], off offset:256
	v_add_co_u32_e32 v244, vcc, 0x40000, v244
	v_mfma_f32_32x32x16_bf16 v[18:33], v[218:221], v[210:213], v[18:33]
	s_waitcnt vmcnt(7)
	ds_write_b128 v242, v[146:149] offset:18432
	v_addc_co_u32_e32 v245, vcc, 0, v245, vcc
	global_load_dwordx4 v[146:149], v[244:245], off offset:256
	v_add_co_u32_e32 v246, vcc, 0x40000, v246
	v_mfma_f32_32x32x16_bf16 v[2:17], v[236:239], v[210:213], v[2:17]
	s_setprio 0
	s_waitcnt vmcnt(7)
	ds_write_b128 v242, v[150:153] offset:55296
	v_addc_co_u32_e32 v247, vcc, 0, v247, vcc
	global_load_dwordx4 v[150:153], v[246:247], off offset:256
	v_add_co_u32_e32 v244, vcc, 0x40000, v244
	s_waitcnt vmcnt(7)
	ds_write_b128 v242, v[154:157] offset:27648
	v_addc_co_u32_e32 v245, vcc, 0, v245, vcc
	global_load_dwordx4 v[154:157], v[244:245], off offset:256
	v_add_co_u32_e32 v246, vcc, 0x40000, v246
	s_waitcnt vmcnt(7)
	ds_write_b128 v242, v[158:161] offset:64512
	v_addc_co_u32_e32 v247, vcc, 0, v247, vcc
	global_load_dwordx4 v[158:161], v[246:247], off offset:256
	s_branch .LBB0_291
; template <bool SWAP, bool SSQ, bool ZERO = true>
; DI void gemm_main(const u16* __restrict__ A, int lda, const u16* __restrict__ Bt, int ldb, int K, char* lds,
;                   f32x16 (&acc)[4][2], float* rs_lds) {
;     ...
;   for (int kt = 0; kt < nk; ++kt) {
;     const int st = (kt & 1) * 2 * G_TILE;
;     {
;       bf16x8 fa[2][4], fb[2][2];
; #pragma unroll
;       for (int i = 0; i < 4; ++i) fa[0][i] = *(const bf16x8*)(abase + st + i * 32 * GS);
; #pragma unroll
;       for (int i = 0; i < 2; ++i) fb[0][i] = *(const bf16x8*)(bbase + st + i * 32 * GS);
; #pragma unroll
;       for (int ks = 0; ks < 4; ++ks) {
;         if (ks + 1 < 4) {
; #pragma unroll
;           for (int i = 0; i < 4; ++i) fa[(ks + 1) & 1][i] = *(const bf16x8*)(abase + st + i * 32 * GS + (ks + 1) * 32);
; #pragma unroll
;           for (int i = 0; i < 2; ++i) fb[(ks + 1) & 1][i] = *(const bf16x8*)(bbase + st + i * 32 * GS + (ks + 1) * 32);
;         }
;         __builtin_amdgcn_sched_barrier(0);
;         __builtin_amdgcn_s_setprio(1);
; #pragma unroll
;         for (int mt = 0; mt < 4; ++mt)
; #pragma unroll
;           for (int nt = 0; nt < 2; ++nt)
;             acc[mt][nt] = SWAP ? MFMA32(fb[ks & 1][nt], fa[ks & 1][mt], acc[mt][nt]) : MFMA32(fa[ks & 1][mt], fb[ks & 1][nt], acc[mt][nt]);
;         __builtin_amdgcn_s_setprio(0);
;         __builtin_amdgcn_sched_barrier(0);
;       }
;     }
;     if (kt + 1 < nk) G_WRITE((kt + 1) & 1);
;     if (kt + 2 < nk) G_LOAD(kt + 2);
;     __syncthreads();
; DI void out_tile(const Params& p, int l, int mi, int ni, char* lds) {
;     ...
; #pragma unroll
;   for (int mt = 0; mt < 4; ++mt) {
;     const size_t rowoff = (size_t)(m0 + wm * 128 + mt * 32 + r) * DM + n0 + wn * 64 + 4 * hf;
;     const size_t rowoffb = (size_t)(m0 + wm * 128 + mt * 32 + r) * DM + n0 + wn * 64 + 8 * hf;
;     float pss = 0.f;
; #pragma unroll
;     for (int nt = 0; nt < 2; ++nt)
; #pragma unroll
;       for (int a = 0; a < 2; ++a) {
;         float xq[2][4];
; #pragma unroll
;         for (int gg = 0; gg < 2; ++gg) {
;           const int g = 2 * a + gg;
;           f32x4 xo = {acc[mt][nt][4 * g], acc[mt][nt][4 * g + 1], acc[mt][nt][4 * g + 2], acc[mt][nt][4 * g + 3]};
;           *(f32x4*)(p.X + rowoff + nt * 32 + 8 * g) = xo;
;           xq[gg][0] = xo[0]; xq[gg][1] = xo[1]; xq[gg][2] = xo[2]; xq[gg][3] = xo[3];
.Lg292_tail:
	s_setprio 1
	s_waitcnt lgkmcnt(4)
	v_mfma_f32_32x32x16_bf16 v[114:129], v[218:221], v[186:189], v[114:129]
	s_waitcnt lgkmcnt(3)
	v_mfma_f32_32x32x16_bf16 v[98:113], v[236:239], v[186:189], v[98:113]
	s_waitcnt lgkmcnt(2)
	v_mfma_f32_32x32x16_bf16 v[82:97], v[218:221], v[194:197], v[82:97]
	v_mfma_f32_32x32x16_bf16 v[66:81], v[236:239], v[194:197], v[66:81]
	s_waitcnt lgkmcnt(1)
	v_mfma_f32_32x32x16_bf16 v[50:65], v[218:221], v[202:205], v[50:65]
	v_mfma_f32_32x32x16_bf16 v[34:49], v[236:239], v[202:205], v[34:49]
	s_waitcnt lgkmcnt(0)
	v_mfma_f32_32x32x16_bf16 v[18:33], v[218:221], v[210:213], v[18:33]
	v_mfma_f32_32x32x16_bf16 v[2:17], v[236:239], v[210:213], v[2:17]
	s_setprio 0
	s_cmpk_eq_i32 s82, 0xf80
	s_cbranch_scc1 .LBB0_294
	s_and_b32 s4, s85, 2
	s_mul_i32 s4, s4, 0x9000
	v_add_u32_e32 v177, s4, v174
	s_waitcnt vmcnt(7)
	ds_write_b128 v177, v[130:133]
	s_waitcnt vmcnt(6)
	ds_write_b128 v177, v[134:137] offset:36864
	s_waitcnt vmcnt(5)
	ds_write_b128 v177, v[138:141] offset:9216
	s_waitcnt vmcnt(4)
	ds_write_b128 v177, v[142:145] offset:46080
	s_waitcnt vmcnt(3)
	ds_write_b128 v177, v[146:149] offset:18432
	s_waitcnt vmcnt(2)
	ds_write_b128 v177, v[150:153] offset:55296
	s_waitcnt vmcnt(1)
	ds_write_b128 v177, v[154:157] offset:27648
	s_waitcnt vmcnt(0)
	ds_write_b128 v177, v[158:161] offset:64512
.LBB0_294:
	s_branch .LBB0_291
.LBB0_296:
	s_waitcnt vmcnt(7)
	v_mov_b32_e32 v131, s1
	v_or_b32_e32 v130, s0, v172
	v_lshlrev_b64 v[132:133], 11, v[168:169]
	s_waitcnt vmcnt(6)
	v_lshl_add_u64 v[136:137], v[132:133], 0, v[130:131]
	v_lshl_add_u64 v[134:135], v[136:137], 2, s[38:39]
	v_lshlrev_b32_e32 v132, 2, v170
	v_mov_b32_e32 v133, v1
	s_waitcnt vmcnt(5)
	v_lshl_add_u64 v[138:139], v[134:135], 0, v[132:133]
	v_fma_f32 v134, v114, v114, 0
	v_fmac_f32_e32 v134, v115, v115
	v_fmac_f32_e32 v134, v116, v116
	v_fmac_f32_e32 v134, v117, v117
	v_fmac_f32_e32 v134, v118, v118
	v_fmac_f32_e32 v134, v119, v119
	v_fmac_f32_e32 v134, v120, v120
	v_fmac_f32_e32 v134, v121, v121
	v_fmac_f32_e32 v134, v122, v122
	v_fmac_f32_e32 v134, v123, v123
	v_fmac_f32_e32 v134, v124, v124
	v_fmac_f32_e32 v134, v125, v125
	v_fmac_f32_e32 v134, v126, v126
	v_fmac_f32_e32 v134, v127, v127
	v_fmac_f32_e32 v134, v128, v128
	v_fmac_f32_e32 v134, v129, v129
	v_fmac_f32_e32 v134, v98, v98
	v_fmac_f32_e32 v134, v99, v99
	v_fmac_f32_e32 v134, v100, v100
	v_fmac_f32_e32 v134, v101, v101
	v_fmac_f32_e32 v134, v102, v102
	v_fmac_f32_e32 v134, v103, v103
	v_fmac_f32_e32 v134, v104, v104
	v_fmac_f32_e32 v134, v105, v105
	v_fmac_f32_e32 v134, v106, v106
	global_store_dwordx4 v[138:139], v[114:117], off
	v_lshl_add_u64 v[136:137], v[136:137], 1, s[40:41]
	v_fmac_f32_e32 v134, v107, v107
	v_cvt_pk_bf16_f32 v114, v114, v115
	v_cvt_pk_bf16_f32 v115, v116, v117
	v_cvt_pk_bf16_f32 v116, v118, v119
	v_cvt_pk_bf16_f32 v117, v120, v121
	v_lshl_add_u64 v[136:137], v[136:137], 0, v[0:1]
	v_permlane32_swap_b32_e32 v114, v116
	v_permlane32_swap_b32_e32 v115, v117
	v_fmac_f32_e32 v134, v108, v108
	global_store_dwordx4 v[138:139], v[118:121], off offset:32
	global_store_dwordx4 v[136:137], v[114:117], off
	global_store_dwordx4 v[138:139], v[122:125], off offset:64
	v_fmac_f32_e32 v134, v109, v109
	v_cvt_pk_bf16_f32 v114, v122, v123
	v_cvt_pk_bf16_f32 v115, v124, v125
	v_cvt_pk_bf16_f32 v116, v126, v127
	v_cvt_pk_bf16_f32 v117, v128, v129
	s_nop 0
	v_permlane32_swap_b32_e32 v114, v116
	v_permlane32_swap_b32_e32 v115, v117
	v_fmac_f32_e32 v134, v110, v110
	global_store_dwordx4 v[138:139], v[126:129], off offset:96
	global_store_dwordx4 v[136:137], v[114:117], off offset:32
	global_store_dwordx4 v[138:139], v[98:101], off offset:128
	v_fmac_f32_e32 v134, v111, v111
	v_fmac_f32_e32 v134, v112, v112
	v_cvt_pk_bf16_f32 v98, v98, v99
	v_cvt_pk_bf16_f32 v99, v100, v101
	v_cvt_pk_bf16_f32 v100, v102, v103
	v_cvt_pk_bf16_f32 v101, v104, v105
	s_nop 0
	v_permlane32_swap_b32_e32 v98, v100
	v_permlane32_swap_b32_e32 v99, v101
	global_store_dwordx4 v[138:139], v[102:105], off offset:160
	global_store_dwordx4 v[136:137], v[98:101], off offset:64
	global_store_dwordx4 v[138:139], v[106:109], off offset:192
	v_fmac_f32_e32 v134, v113, v113
	v_cvt_pk_bf16_f32 v98, v106, v107
	v_cvt_pk_bf16_f32 v99, v108, v109
	v_cvt_pk_bf16_f32 v100, v110, v111
	v_cvt_pk_bf16_f32 v101, v112, v113
	s_lshl_b32 s0, s84, 2
	v_permlane32_swap_b32_e32 v98, v100
	v_permlane32_swap_b32_e32 v99, v101
	v_mov_b32_e32 v0, v134
	v_cmp_eq_u32_e32 vcc, 0, v171
	s_ashr_i32 s1, s0, 31
	global_store_dwordx4 v[138:139], v[110:113], off offset:224
	global_store_dwordx4 v[136:137], v[98:101], off offset:96
	v_permlane32_swap_b32_e32 v134, v0
	s_nop 0
	v_lshlrev_b32_e32 v98, 2, v173
	s_and_saveexec_b64 s[82:83], vcc
	s_cbranch_execz .LBB0_298
	v_lshlrev_b64 v[100:101], 7, v[168:169]
	v_lshl_add_u64 v[100:101], s[28:29], 0, v[100:101]
	v_lshl_add_u64 v[100:101], s[0:1], 2, v[100:101]
	v_mov_b32_e32 v99, v1
	v_lshl_add_u64 v[100:101], v[100:101], 0, v[98:99]
	v_add_f32_e32 v0, v134, v0
	global_store_dword v[100:101], v0, off

; __global__ void __launch_bounds__(NTHREADS, 2) fwd_kernel(Params p) {
;   __shared__ __attribute__((aligned(16))) char lds[LDS_BYTES];
	.amdhsa_kernel _Z10fwd_kernel6Params
		.amdhsa_group_segment_fixed_size 148480
		.amdhsa_private_segment_fixed_size 0
		.amdhsa_kernarg_size 544
		.amdhsa_user_sgpr_count 2
		.amdhsa_user_sgpr_dispatch_ptr 0
		.amdhsa_user_sgpr_queue_ptr 0
		.amdhsa_user_sgpr_kernarg_segment_ptr 1
		.amdhsa_user_sgpr_dispatch_id 0
		.amdhsa_user_sgpr_kernarg_preload_length 0
		.amdhsa_user_sgpr_kernarg_preload_offset 0
		.amdhsa_user_sgpr_private_segment_size 0
		.amdhsa_uses_dynamic_stack 0
		.amdhsa_enable_private_segment 0
		.amdhsa_system_sgpr_workgroup_id_x 1
		.amdhsa_system_sgpr_workgroup_id_y 0
		.amdhsa_system_sgpr_workgroup_id_z 0
		.amdhsa_system_sgpr_workgroup_info 0
		.amdhsa_system_vgpr_workitem_id 2
		.amdhsa_next_free_vgpr 248
		.amdhsa_next_free_sgpr 100
		.amdhsa_accum_offset 248
		.amdhsa_reserve_vcc 1
		.amdhsa_float_round_mode_32 0
		.amdhsa_float_round_mode_16_64 0
		.amdhsa_float_denorm_mode_32 3
		.amdhsa_float_denorm_mode_16_64 3
		.amdhsa_dx10_clamp 1
		.amdhsa_ieee_mode 1
		.amdhsa_fp16_overflow 0
		.amdhsa_tg_split 0
		.amdhsa_exception_fp_ieee_invalid_op 0
		.amdhsa_exception_fp_denorm_src 0
		.amdhsa_exception_fp_ieee_div_zero 0
		.amdhsa_exception_fp_ieee_overflow 0
		.amdhsa_exception_fp_ieee_underflow 0
		.amdhsa_exception_fp_ieee_inexact 0
		.amdhsa_exception_int_div_zero 0
	.end_amdhsa_kernel

; __global__ void __launch_bounds__(NTHREADS, 2) fwd_kernel(Params p) {
;   __shared__ __attribute__((aligned(16))) char lds[LDS_BYTES];
.Lfunc_end0:
	.size	_Z10fwd_kernel6Params, .Lfunc_end0-_Z10fwd_kernel6Params
	.set _Z10fwd_kernel6Params.num_vgpr, 248
	.set _Z10fwd_kernel6Params.num_agpr, 0
	.set _Z10fwd_kernel6Params.numbered_sgpr, 100
	.set _Z10fwd_kernel6Params.num_named_barrier, 0
	.set _Z10fwd_kernel6Params.private_seg_size, 0
	.set _Z10fwd_kernel6Params.uses_vcc, 1
	.set _Z10fwd_kernel6Params.uses_flat_scratch, 0
	.set _Z10fwd_kernel6Params.has_dyn_sized_stack, 0
	.set _Z10fwd_kernel6Params.has_recursion, 0
	.set _Z10fwd_kernel6Params.has_indirect_call, 0

; __global__ void __launch_bounds__(NTHREADS, 2) fwd_kernel(Params p) {
;   __shared__ __attribute__((aligned(16))) char lds[LDS_BYTES];
amdhsa.kernels:
  - .agpr_count:     0
    .args:
      - .offset:         0
        .size:           288
        .value_kind:     by_value
      - .offset:         288
        .size:           4
        .value_kind:     hidden_block_count_x
      - .offset:         292
        .size:           4
        .value_kind:     hidden_block_count_y
      - .offset:         296
        .size:           4
        .value_kind:     hidden_block_count_z
      - .offset:         300
        .size:           2
        .value_kind:     hidden_group_size_x
      - .offset:         302
        .size:           2
        .value_kind:     hidden_group_size_y
      - .offset:         304
        .size:           2
        .value_kind:     hidden_group_size_z
      - .offset:         306
        .size:           2
        .value_kind:     hidden_remainder_x
      - .offset:         308
        .size:           2
        .value_kind:     hidden_remainder_y
      - .offset:         310
        .size:           2
        .value_kind:     hidden_remainder_z
      - .offset:         328
        .size:           8
        .value_kind:     hidden_global_offset_x
      - .offset:         336
        .size:           8
        .value_kind:     hidden_global_offset_y
      - .offset:         344
        .size:           8
        .value_kind:     hidden_global_offset_z
      - .offset:         352
        .size:           2
        .value_kind:     hidden_grid_dims
      - .offset:         376
        .size:           8
        .value_kind:     hidden_multigrid_sync_arg
    .group_segment_fixed_size: 148480
    .kernarg_segment_align: 8
    .kernarg_segment_size: 544
    .language:       OpenCL C
    .language_version:
      - 2
      - 0
    .max_flat_workgroup_size: 512
    .name:           _Z10fwd_kernel6Params
    .private_segment_fixed_size: 0
    .sgpr_count:     106
    .sgpr_spill_count: 42
    .symbol:         _Z10fwd_kernel6Params.kd
    .uniform_work_group_size: 1
    .uses_dynamic_stack: false
    .vgpr_count:     248
    .vgpr_spill_count: 0
    .wavefront_size: 64
